# v45 with the barrier #3 weight touch restricted to w_out + w_up (10 MiB instead of 20: w_down / w_ple_gate are touched at the P5 / P6 waits; LLC is full at the end of P2)
# speedup vs baseline: 1.0056x; 1.0056x over previous
.LBB0_487:
	v_readlane_b32 s72, v251, 2
	v_readlane_b32 s73, v251, 3
	s_cmp_lt_i32 s73, 4
	v_readlane_b32 s68, v250, 14
	v_readlane_b32 s74, v251, 4
	v_readlane_b32 s75, v251, 5
	s_cbranch_scc1 .LBB0_541
	s_waitcnt vmcnt(0)
	s_barrier
	v_readfirstlane_b32 s1, v0
	s_cmp_lt_u32 s1, 64
	s_cbranch_scc1 .Lmy_touchw_skip
	v_readlane_b32 s98, v251, 20
	v_readlane_b32 s99, v251, 21
	s_mul_i32 s0, s70, 0xa000
	s_add_u32 s0, s0, 0x800000
	s_add_u32 s98, s98, s0
	s_addc_u32 s99, s99, 0
	v_add_u32_e32 v252, 0xffffffc0, v0
	v_lshlrev_b32_e32 v252, 6, v252
	s_nop 1
	global_load_dword v255, v252, s[98:99]
	v_add_u32_e32 v253, 0x7000, v252
	global_load_dword v255, v253, s[98:99]
